# attention D loop: cross-half max exchange via v_permlane32_swap instead of ds_bpermute
# speedup vs baseline: 1.0051x; 1.0027x over previous
; DI void attn_item(const Params& P, unsigned char* smem, bool samp, int b, int c) {
;     ...
;       const int mw = (int)(maskl[(kt * 64 + qh * 32 + l32) * 2 + kh] >> (4 * g));
;       const int relb = (int)key0 + 4 * g - (qpos0 + qh * 32 + l32) + T5OFF;
;       float mx = -1e30f;
;       if (!farT) {
;         for (int r = 0; r < 16; ++r) sacc[qh][r] += t5l[relb + (r & 3) + 8 * (r >> 2)];
;       }
;       for (int r = 0; r < 16; ++r) {
;         float l = sacc[qh][r];
;         const unsigned keep = (unsigned)__builtin_amdgcn_sbfe(mw, (r & 3) + 8 * (r >> 2), 1);
;         l = __uint_as_float((__float_as_uint(l) & keep) | (0xFF800000u & ~keep));
;         sacc[qh][r] = l;
;         mx = fmaxf(mx, l);
;       }
;       mx = fmaxf(mx, __shfl_xor(mx, 32));
;       if (__ballot(mx > mrun[qh]) != 0ull) {
;         const float mnew = fmaxf(mrun[qh], mx);
;         const float alpha = __builtin_amdgcn_exp2f(mrun[qh] - mnew);
;         mrun[qh] = mnew;
;         lrun[qh] *= alpha;
;         for (int dh = 0; dh < 2; ++dh)
;           for (int r = 0; r < 16; ++r) oacc[dh][qh][r] *= alpha;
;       }
.LBB0_701:
	s_waitcnt lgkmcnt(0)
	v_lshrrev_b32_e32 v202, v198, v5
	v_bfe_i32 v5, v202, 0, 1
	v_bfe_i32 v6, v202, 1, 1
	v_bitop3_b32 v5, v98, s93, v5 bitop3:0xe4
	v_bitop3_b32 v6, v99, s93, v6 bitop3:0xe4
	v_bfe_i32 v7, v202, 2, 1
	v_bfe_i32 v8, v202, 3, 1
	v_max3_f32 v9, v5, s4, v6
	v_bitop3_b32 v7, v100, s93, v7 bitop3:0xe4
	v_bitop3_b32 v8, v101, s93, v8 bitop3:0xe4
	v_max3_f32 v11, v9, v7, v8
	v_bfe_i32 v9, v202, 8, 1
	v_bfe_i32 v10, v202, 9, 1
	v_bitop3_b32 v9, v102, s93, v9 bitop3:0xe4
	v_bitop3_b32 v10, v103, s93, v10 bitop3:0xe4
	v_max3_f32 v13, v11, v9, v10
	v_bfe_i32 v11, v202, 10, 1
	v_bfe_i32 v12, v202, 11, 1
	v_bitop3_b32 v11, v104, s93, v11 bitop3:0xe4
	v_bitop3_b32 v12, v105, s93, v12 bitop3:0xe4
	v_max3_f32 v15, v13, v11, v12
	v_bfe_i32 v13, v202, 16, 1
	v_bfe_i32 v14, v202, 17, 1
	v_bitop3_b32 v13, v106, s93, v13 bitop3:0xe4
	v_bitop3_b32 v14, v107, s93, v14 bitop3:0xe4
	v_max3_f32 v17, v15, v13, v14
	v_bfe_i32 v15, v202, 18, 1
	v_bfe_i32 v16, v202, 19, 1
	v_bitop3_b32 v15, v108, s93, v15 bitop3:0xe4
	v_bitop3_b32 v16, v109, s93, v16 bitop3:0xe4
	v_max3_f32 v99, v17, v15, v16
	v_bfe_i32 v17, v202, 24, 1
	v_bfe_i32 v98, v202, 25, 1
	v_bitop3_b32 v17, v110, s93, v17 bitop3:0xe4
	v_bitop3_b32 v98, v111, s93, v98 bitop3:0xe4
	v_max3_f32 v101, v99, v17, v98
	v_bfe_i32 v99, v202, 26, 1
	v_bfe_i32 v100, v202, 27, 1
	v_bitop3_b32 v99, v112, s93, v99 bitop3:0xe4
	v_bitop3_b32 v100, v113, s93, v100 bitop3:0xe4
	v_max3_f32 v101, v101, v99, v100
	v_mov_b32_e32 v102, v101
	s_nop 1
	v_permlane32_swap_b32_e32 v101, v102
	s_nop 0
	v_max_f32_e32 v101, v101, v102
	v_cmp_gt_f32_e32 vcc, v101, v2
	s_cbranch_vccz .LBB0_703
	v_max_f32_e32 v101, v101, v101
	v_max_f32_e32 v102, v2, v2
	v_max_f32_e32 v101, v102, v101
	v_sub_f32_e32 v2, v2, v101
	v_exp_f32_e32 v2, v2
	s_nop 0
	v_mul_f32_e32 v4, v4, v2
	v_pk_mul_f32 v[80:81], v[80:81], v[2:3] op_sel_hi:[1,0]
	v_pk_mul_f32 v[78:79], v[78:79], v[2:3] op_sel_hi:[1,0]
	v_pk_mul_f32 v[76:77], v[76:77], v[2:3] op_sel_hi:[1,0]
	v_pk_mul_f32 v[74:75], v[74:75], v[2:3] op_sel_hi:[1,0]
	v_pk_mul_f32 v[72:73], v[72:73], v[2:3] op_sel_hi:[1,0]
	v_pk_mul_f32 v[70:71], v[70:71], v[2:3] op_sel_hi:[1,0]
	v_pk_mul_f32 v[68:69], v[68:69], v[2:3] op_sel_hi:[1,0]
	v_pk_mul_f32 v[66:67], v[66:67], v[2:3] op_sel_hi:[1,0]
	v_pk_mul_f32 v[64:65], v[64:65], v[2:3] op_sel_hi:[1,0]
	v_pk_mul_f32 v[62:63], v[62:63], v[2:3] op_sel_hi:[1,0]
	v_pk_mul_f32 v[60:61], v[60:61], v[2:3] op_sel_hi:[1,0]
	v_pk_mul_f32 v[58:59], v[58:59], v[2:3] op_sel_hi:[1,0]
	v_pk_mul_f32 v[56:57], v[56:57], v[2:3] op_sel_hi:[1,0]
	v_pk_mul_f32 v[54:55], v[54:55], v[2:3] op_sel_hi:[1,0]
	v_pk_mul_f32 v[52:53], v[52:53], v[2:3] op_sel_hi:[1,0]
	v_pk_mul_f32 v[50:51], v[50:51], v[2:3] op_sel_hi:[1,0]
	v_cndmask_b32_e64 v2, v101, 0, vcc
	v_cndmask_b32_e64 v101, 0, v101, vcc
	v_sub_f32_e32 v5, v5, v101
	v_sub_f32_e32 v6, v6, v101
	v_sub_f32_e32 v7, v7, v101
	v_sub_f32_e32 v8, v8, v101
	v_sub_f32_e32 v9, v9, v101
	v_sub_f32_e32 v10, v10, v101
	v_sub_f32_e32 v11, v11, v101
	v_sub_f32_e32 v12, v12, v101
	v_sub_f32_e32 v13, v13, v101
	v_sub_f32_e32 v14, v14, v101
	v_sub_f32_e32 v15, v15, v101
	v_sub_f32_e32 v16, v16, v101
	v_sub_f32_e32 v17, v17, v101
	v_sub_f32_e32 v98, v98, v101
	v_sub_f32_e32 v99, v99, v101
	v_sub_f32_e32 v100, v100, v101
	v_sub_f32_e32 v204, v204, v101
	v_sub_f32_e32 v205, v205, v101
	v_sub_f32_e32 v206, v206, v101
	v_sub_f32_e32 v207, v207, v101
	v_sub_f32_e32 v208, v208, v101
	v_sub_f32_e32 v209, v209, v101
	v_sub_f32_e32 v210, v210, v101
	v_sub_f32_e32 v211, v211, v101
	v_sub_f32_e32 v212, v212, v101
	v_sub_f32_e32 v213, v213, v101
	v_sub_f32_e32 v214, v214, v101
	v_sub_f32_e32 v215, v215, v101
	v_sub_f32_e32 v216, v216, v101
	v_sub_f32_e32 v217, v217, v101
	v_sub_f32_e32 v218, v218, v101
	v_sub_f32_e32 v219, v219, v101

; DI void attn_item(const Params& P, unsigned char* smem, bool samp, int b, int c) {
;     ...
;       const int mw = (int)(maskl[(kt * 64 + qh * 32 + l32) * 2 + kh] >> (4 * g));
;       const int relb = (int)key0 + 4 * g - (qpos0 + qh * 32 + l32) + T5OFF;
;       float mx = -1e30f;
;       if (!farT) {
;         for (int r = 0; r < 16; ++r) sacc[qh][r] += t5l[relb + (r & 3) + 8 * (r >> 2)];
;       }
;       for (int r = 0; r < 16; ++r) {
;         float l = sacc[qh][r];
;         const unsigned keep = (unsigned)__builtin_amdgcn_sbfe(mw, (r & 3) + 8 * (r >> 2), 1);
;         l = __uint_as_float((__float_as_uint(l) & keep) | (0xFF800000u & ~keep));
;         sacc[qh][r] = l;
;         mx = fmaxf(mx, l);
;       }
;       mx = fmaxf(mx, __shfl_xor(mx, 32));
;       if (__ballot(mx > mrun[qh]) != 0ull) {
;         const float mnew = fmaxf(mrun[qh], mx);
;         const float alpha = __builtin_amdgcn_exp2f(mrun[qh] - mnew);
;         mrun[qh] = mnew;
;         lrun[qh] *= alpha;
;         for (int dh = 0; dh < 2; ++dh)
;           for (int r = 0; r < 16; ++r) oacc[dh][qh][r] *= alpha;
;       }
.LBB0_705:
	s_waitcnt lgkmcnt(0)
	v_lshrrev_b32_e32 v110, v198, v101
	v_bfe_i32 v101, v110, 0, 1
	v_bitop3_b32 v109, v82, s93, v101 bitop3:0xe4
	v_bfe_i32 v82, v110, 1, 1
	v_bitop3_b32 v105, v83, s93, v82 bitop3:0xe4
	v_bfe_i32 v83, v110, 2, 1
	v_bitop3_b32 v106, v84, s93, v83 bitop3:0xe4
	v_bfe_i32 v83, v110, 3, 1
	v_bitop3_b32 v107, v85, s93, v83 bitop3:0xe4
	v_bfe_i32 v83, v110, 8, 1
	v_bitop3_b32 v108, v86, s93, v83 bitop3:0xe4
	v_bfe_i32 v83, v110, 9, 1
	v_bitop3_b32 v104, v87, s93, v83 bitop3:0xe4
	v_bfe_i32 v83, v110, 10, 1
	v_bitop3_b32 v101, v88, s93, v83 bitop3:0xe4
	v_bfe_i32 v83, v110, 11, 1
	v_max3_f32 v82, v109, s4, v105
	v_bitop3_b32 v102, v89, s93, v83 bitop3:0xe4
	v_bfe_i32 v83, v110, 16, 1
	v_max3_f32 v82, v82, v106, v107
	v_bitop3_b32 v103, v90, s93, v83 bitop3:0xe4
	v_bfe_i32 v83, v110, 17, 1
	v_max3_f32 v82, v82, v108, v104
	v_bitop3_b32 v91, v91, s93, v83 bitop3:0xe4
	v_bfe_i32 v83, v110, 18, 1
	v_max3_f32 v82, v82, v101, v102
	v_bitop3_b32 v87, v92, s93, v83 bitop3:0xe4
	v_bfe_i32 v83, v110, 19, 1
	v_max3_f32 v82, v82, v103, v91
	v_bitop3_b32 v83, v93, s93, v83 bitop3:0xe4
	v_bfe_i32 v84, v110, 24, 1
	v_bfe_i32 v85, v110, 25, 1
	v_max3_f32 v82, v82, v87, v83
	v_bitop3_b32 v84, v94, s93, v84 bitop3:0xe4
	v_bitop3_b32 v85, v95, s93, v85 bitop3:0xe4
	v_max3_f32 v88, v82, v84, v85
	v_bfe_i32 v82, v110, 26, 1
	v_bitop3_b32 v86, v96, s93, v82 bitop3:0xe4
	v_bfe_i32 v82, v110, 27, 1
	v_bitop3_b32 v82, v97, s93, v82 bitop3:0xe4
	v_max3_f32 v88, v88, v86, v82
	v_mov_b32_e32 v89, v88
	s_nop 1
	v_permlane32_swap_b32_e32 v88, v89
	s_nop 0
	v_max_f32_e32 v88, v88, v89
	v_cmp_gt_f32_e32 vcc, v88, v201
	s_cbranch_vccz .LBB0_707
	v_max_f32_e32 v88, v88, v88
	v_max_f32_e32 v89, v201, v201
	v_max_f32_e32 v89, v89, v88
	v_sub_f32_e32 v88, v201, v89
	v_exp_f32_e32 v88, v88
	s_nop 0
	v_mul_f32_e32 v197, v197, v88
	v_pk_mul_f32 v[48:49], v[48:49], v[88:89] op_sel_hi:[1,0]
	v_pk_mul_f32 v[46:47], v[46:47], v[88:89] op_sel_hi:[1,0]
	v_pk_mul_f32 v[44:45], v[44:45], v[88:89] op_sel_hi:[1,0]
	v_pk_mul_f32 v[42:43], v[42:43], v[88:89] op_sel_hi:[1,0]
	v_pk_mul_f32 v[40:41], v[40:41], v[88:89] op_sel_hi:[1,0]
	v_pk_mul_f32 v[38:39], v[38:39], v[88:89] op_sel_hi:[1,0]
	v_pk_mul_f32 v[36:37], v[36:37], v[88:89] op_sel_hi:[1,0]
	v_pk_mul_f32 v[34:35], v[34:35], v[88:89] op_sel_hi:[1,0]
	v_pk_mul_f32 v[32:33], v[32:33], v[88:89] op_sel_hi:[1,0]
	v_pk_mul_f32 v[30:31], v[30:31], v[88:89] op_sel_hi:[1,0]
	v_pk_mul_f32 v[28:29], v[28:29], v[88:89] op_sel_hi:[1,0]
	v_pk_mul_f32 v[26:27], v[26:27], v[88:89] op_sel_hi:[1,0]
	v_pk_mul_f32 v[24:25], v[24:25], v[88:89] op_sel_hi:[1,0]
	v_pk_mul_f32 v[22:23], v[22:23], v[88:89] op_sel_hi:[1,0]
	v_pk_mul_f32 v[20:21], v[20:21], v[88:89] op_sel_hi:[1,0]
	v_pk_mul_f32 v[18:19], v[18:19], v[88:89] op_sel_hi:[1,0]
	v_cndmask_b32_e64 v201, v89, 0, vcc
	v_cndmask_b32_e64 v89, 0, v89, vcc
	v_sub_f32_e32 v109, v109, v89
	v_sub_f32_e32 v105, v105, v89
	v_sub_f32_e32 v106, v106, v89
	v_sub_f32_e32 v107, v107, v89
	v_sub_f32_e32 v108, v108, v89
	v_sub_f32_e32 v104, v104, v89
	v_sub_f32_e32 v101, v101, v89
	v_sub_f32_e32 v102, v102, v89
	v_sub_f32_e32 v103, v103, v89
	v_sub_f32_e32 v91, v91, v89
	v_sub_f32_e32 v87, v87, v89
	v_sub_f32_e32 v83, v83, v89
	v_sub_f32_e32 v84, v84, v89
	v_sub_f32_e32 v85, v85, v89
	v_sub_f32_e32 v86, v86, v89
	v_sub_f32_e32 v82, v82, v89
	v_sub_f32_e32 v220, v220, v89
	v_sub_f32_e32 v221, v221, v89
	v_sub_f32_e32 v222, v222, v89
	v_sub_f32_e32 v223, v223, v89
	v_sub_f32_e32 v224, v224, v89
	v_sub_f32_e32 v225, v225, v89
	v_sub_f32_e32 v226, v226, v89
	v_sub_f32_e32 v227, v227, v89
	v_sub_f32_e32 v228, v228, v89
	v_sub_f32_e32 v229, v229, v89
	v_sub_f32_e32 v230, v230, v89
	v_sub_f32_e32 v231, v231, v89
	v_sub_f32_e32 v232, v232, v89
	v_sub_f32_e32 v233, v233, v89
	v_sub_f32_e32 v234, v234, v89
	v_sub_f32_e32 v235, v235, v89
